# hand-written hot-loop heads aligned to 64 bytes (code placement), on top of lower-half static priority
# baseline (speedup 1.0000x reference)
; DI float bf2f(bf16_t b) { return __uint_as_float(((unsigned)b) << 16); }
; DI float softplusf_(float z) { return fmaxf(z, 0.f) + __logf(1.f + __expf(-fabsf(z))); }
; template <bool PASS2>
; DI void lru_item(const Params& p, int l, int item, int lane, const bf16_t* xl, float* wxs) {
;     ...
;   const float sp = softplusf_(-p.in[I_LRU_LAM][l * 512 + ch]);
;   const size_t tok0 = (size_t)b * SEQ + (size_t)c * LCL;
;   float x1 = 0.f, x2 = 0.f, x3 = 0.f;
;   if (c > 0) {
;     x1 = bf2f(xl[(tok0 - 1) * 512 + ch]); x2 = bf2f(xl[(tok0 - 2) * 512 + ch]); x3 = bf2f(xl[(tok0 - 3) * 512 + ch]);
;   }
;   float* st = p.lrust + ((size_t)(b * 512 + ch) * NCHL + c) * 2;
;   float hs = PASS2 ? st[1] : 0.f;
;   float aprod = 1.f;
;   float xn = bf2f(xl[tok0 * 512 + ch]);
; #pragma unroll 1
.Llrua1_nohist:
	global_load_ushort v20, v73, s[6:7] offset:0
	global_load_ushort v21, v73, s[6:7] offset:1024
	global_load_ushort v22, v73, s[6:7] offset:2048
	global_load_ushort v23, v73, s[6:7] offset:3072
	v_add_u32_e32 v73, 0x1000, v73
	global_load_ushort v24, v73, s[6:7] offset:0
	global_load_ushort v25, v73, s[6:7] offset:1024
	global_load_ushort v26, v73, s[6:7] offset:2048
	global_load_ushort v27, v73, s[6:7] offset:3072
	v_add_u32_e32 v73, 0x1000, v73
	global_load_ushort v28, v73, s[6:7] offset:0
	global_load_ushort v29, v73, s[6:7] offset:1024
	global_load_ushort v30, v73, s[6:7] offset:2048
	global_load_ushort v31, v73, s[6:7] offset:3072
	v_add_u32_e32 v73, 0x1000, v73
	global_load_ushort v32, v73, s[6:7] offset:0
	global_load_ushort v33, v73, s[6:7] offset:1024
	global_load_ushort v34, v73, s[6:7] offset:2048
	global_load_ushort v35, v73, s[6:7] offset:3072
	v_add_u32_e32 v73, 0x1000, v73
	s_waitcnt vmcnt(0)
	v_lshlrev_b32_e32 v69, 16, v69
	v_lshlrev_b32_e32 v70, 16, v70
	v_lshlrev_b32_e32 v71, 16, v71
	v_and_b32_e32 v146, 0x7fffffff, v15
	v_mul_f32_e32 v146, 0xbfb8aa3b, v146
	v_exp_f32_e32 v146, v146
	v_max_f32_e64 v80, -v15, 0
	v_add_f32_e32 v146, 1.0, v146
	v_log_f32_e32 v146, v146
	s_nop 0
	v_mul_f32_e32 v146, 0x3f317218, v146
	v_add_f32_e32 v146, v80, v146
	v_mul_f32_e32 v15, 0xc138aa3b, v146
	s_mov_b32 s20, 0
	s_movk_i32 s1, 0x7fff
	.p2align	6

; DI float bf2f(bf16_t b) { return __uint_as_float(((unsigned)b) << 16); }
; DI float softplusf_(float z) { return fmaxf(z, 0.f) + __logf(1.f + __expf(-fabsf(z))); }
; template <bool PASS2>
; DI void lru_item(const Params& p, int l, int item, int lane, const bf16_t* xl, float* wxs) {
;     ...
;   const float sp = softplusf_(-p.in[I_LRU_LAM][l * 512 + ch]);
;   const size_t tok0 = (size_t)b * SEQ + (size_t)c * LCL;
;   float x1 = 0.f, x2 = 0.f, x3 = 0.f;
;   if (c > 0) {
;     x1 = bf2f(xl[(tok0 - 1) * 512 + ch]); x2 = bf2f(xl[(tok0 - 2) * 512 + ch]); x3 = bf2f(xl[(tok0 - 3) * 512 + ch]);
;   }
;   float* st = p.lrust + ((size_t)(b * 512 + ch) * NCHL + c) * 2;
;   float hs = PASS2 ? st[1] : 0.f;
;   float aprod = 1.f;
;   float xn = bf2f(xl[tok0 * 512 + ch]);
; #pragma unroll 1
.Llrua2_nohist:
	global_load_ushort v114, v105, s[6:7] offset:0
	global_load_ushort v115, v105, s[6:7] offset:1024
	global_load_ushort v116, v105, s[6:7] offset:2048
	global_load_ushort v117, v105, s[6:7] offset:3072
	v_add_u32_e32 v105, 0x1000, v105
	global_load_ushort v118, v105, s[6:7] offset:0
	global_load_ushort v119, v105, s[6:7] offset:1024
	global_load_ushort v120, v105, s[6:7] offset:2048
	global_load_ushort v121, v105, s[6:7] offset:3072
	v_add_u32_e32 v105, 0x1000, v105
	global_load_ushort v122, v105, s[6:7] offset:0
	global_load_ushort v123, v105, s[6:7] offset:1024
	global_load_ushort v124, v105, s[6:7] offset:2048
	global_load_ushort v125, v105, s[6:7] offset:3072
	v_add_u32_e32 v105, 0x1000, v105
	global_load_ushort v126, v105, s[6:7] offset:0
	global_load_ushort v127, v105, s[6:7] offset:1024
	global_load_ushort v128, v105, s[6:7] offset:2048
	global_load_ushort v129, v105, s[6:7] offset:3072
	v_add_u32_e32 v105, 0x1000, v105
	s_waitcnt vmcnt(0)
	v_lshlrev_b32_e32 v18, 16, v18
	v_lshlrev_b32_e32 v19, 16, v19
	v_lshlrev_b32_e32 v23, 16, v23
	v_and_b32_e32 v146, 0x7fffffff, v15
	v_mul_f32_e32 v146, 0xbfb8aa3b, v146
	v_exp_f32_e32 v146, v146
	v_max_f32_e64 v112, -v15, 0
	v_add_f32_e32 v146, 1.0, v146
	v_log_f32_e32 v146, v146
	s_nop 0
	v_mul_f32_e32 v146, 0x3f317218, v146
	v_add_f32_e32 v146, v112, v146
	v_mul_f32_e32 v15, 0xc138aa3b, v146
	s_mov_b32 s20, 0
	s_movk_i32 s1, 0x7fff
	.p2align	6

; DI float bf2f(bf16_t b) { return __uint_as_float(((unsigned)b) << 16); }
; template <bool PASS2>
; DI void rwkv_item(const Params& p, int l, int item, int lane, const bf16_t* rkv, const bf16_t* lo2, float* rwst) {
;     ...
;   float S[64], P[64];
; #pragma unroll
;   for (int j = 0; j < 64; j++) { S[j] = 0.f; P[j] = (j == lane) ? 1.f : 0.f; }
;   if (PASS2 && c > 0) {
;     const float4* sp = (const float4*)(stS - 4096 + lane * 64);
; #pragma unroll
;     for (int j = 0; j < 16; j++) { float4 v = sp[j]; S[4 * j] = v.x; S[4 * j + 1] = v.y; S[4 * j + 2] = v.z; S[4 * j + 3] = v.w; }
;   }
;   float rp_prev = 0.f, kp_prev = 0.f;
;   if (c > 0) { rp_prev = bf2f(rkv[(tok0 - 1) * 1536 + ch]); kp_prev = bf2f(rkv[(tok0 - 1) * 1536 + 512 + ch]); }
;   const bf16_t* ewb = lo2; const bf16_t* ab = lo2 + (size_t)TOK * 512; const bf16_t* gb = lo2 + (size_t)2 * TOK * 512;
;   struct Raw { bf16_t rp, kp, v, ew, a, g; };
;   struct Der { float rr, wdec, kf, av, bv, v, gg; };
;   auto load_raw = [&](size_t tk) __attribute__((always_inline)) {
;     Raw x;
;     x.rp = rkv[tk * 1536 + ch]; x.kp = rkv[tk * 1536 + 512 + ch]; x.v = p.vbuf[tk * 512 + ch];
;     x.ew = ewb[tk * 512 + ch]; x.a = ab[tk * 512 + ch]; x.g = PASS2 ? gb[tk * 512 + ch] : (bf16_t)0;
;     return x;
;   };
;   auto derive = [&](const Raw& x, float rpp, float kpp) __attribute__((always_inline)) {
;     Der d;
;     const float rp = bf2f(x.rp), kp = bf2f(x.kp), a = bf2f(x.a);
;     d.rr = rp + (rpp - rp) * mu_r;
;     const float k = kp + (kpp - kp) * mu_k;
;     d.wdec = __expf(-bf2f(x.ew));
;     float kkv = k * kkw;
;     const float nrm = wave_sum(kkv * kkv);
;     kkv *= rsqrtf(fmaxf(nrm, 1e-24f));
;     d.kf = k * (1.f + (a - 1.f) * kaw);
;     d.av = -kkv; d.bv = kkv * a;
;     d.v = bf2f(x.v); d.gg = bf2f(x.g);
;     return d;
;   };
;   Raw rawB = load_raw(tok0);
;   Der cur = derive(rawB, rp_prev, kp_prev);
;   float rpA = bf2f(rawB.rp), kpA = bf2f(rawB.kp);
;   rawB = load_raw(tok0 + 1);
.Lrwp1a_noprev:
	v_mov_b32_e32 v64, 0
	v_cmp_eq_u32_e64 s[28:29], 0, v27
	s_nop 1
	v_cndmask_b32_e64 v128, 0, 1.0, s[28:29]
	v_mov_b32_e32 v65, 0
	v_cmp_eq_u32_e64 s[28:29], 1, v27
	s_nop 1
	v_cndmask_b32_e64 v129, 0, 1.0, s[28:29]
	v_mov_b32_e32 v66, 0
	v_cmp_eq_u32_e64 s[28:29], 2, v27
	s_nop 1
	v_cndmask_b32_e64 v130, 0, 1.0, s[28:29]
	v_mov_b32_e32 v67, 0
	v_cmp_eq_u32_e64 s[28:29], 3, v27
	s_nop 1
	v_cndmask_b32_e64 v131, 0, 1.0, s[28:29]
	v_mov_b32_e32 v68, 0
	v_cmp_eq_u32_e64 s[28:29], 8, v27
	s_nop 1
	v_cndmask_b32_e64 v132, 0, 1.0, s[28:29]
	v_mov_b32_e32 v69, 0
	v_cmp_eq_u32_e64 s[28:29], 9, v27
	s_nop 1
	v_cndmask_b32_e64 v133, 0, 1.0, s[28:29]
	v_mov_b32_e32 v70, 0
	v_cmp_eq_u32_e64 s[28:29], 10, v27
	s_nop 1
	v_cndmask_b32_e64 v134, 0, 1.0, s[28:29]
	v_mov_b32_e32 v71, 0
	v_cmp_eq_u32_e64 s[28:29], 11, v27
	s_nop 1
	v_cndmask_b32_e64 v135, 0, 1.0, s[28:29]
	v_mov_b32_e32 v72, 0
	v_cmp_eq_u32_e64 s[28:29], 16, v27
	s_nop 1
	v_cndmask_b32_e64 v136, 0, 1.0, s[28:29]
	v_mov_b32_e32 v73, 0
	v_cmp_eq_u32_e64 s[28:29], 17, v27
	s_nop 1
	v_cndmask_b32_e64 v137, 0, 1.0, s[28:29]
	v_mov_b32_e32 v74, 0
	v_cmp_eq_u32_e64 s[28:29], 18, v27
	s_nop 1
	v_cndmask_b32_e64 v138, 0, 1.0, s[28:29]
	v_mov_b32_e32 v75, 0
	v_cmp_eq_u32_e64 s[28:29], 19, v27
	s_nop 1
	v_cndmask_b32_e64 v139, 0, 1.0, s[28:29]
	v_mov_b32_e32 v76, 0
	v_cmp_eq_u32_e64 s[28:29], 24, v27
	s_nop 1
	v_cndmask_b32_e64 v140, 0, 1.0, s[28:29]
	v_mov_b32_e32 v77, 0
	v_cmp_eq_u32_e64 s[28:29], 25, v27
	s_nop 1
	v_cndmask_b32_e64 v141, 0, 1.0, s[28:29]
	v_mov_b32_e32 v78, 0
	v_cmp_eq_u32_e64 s[28:29], 26, v27
	s_nop 1
	v_cndmask_b32_e64 v142, 0, 1.0, s[28:29]
	v_mov_b32_e32 v79, 0
	v_cmp_eq_u32_e64 s[28:29], 27, v27
	s_nop 1
	v_cndmask_b32_e64 v143, 0, 1.0, s[28:29]
	v_mov_b32_e32 v80, 0
	v_mov_b32_e32 v144, 0
	v_mov_b32_e32 v81, 0
	v_mov_b32_e32 v145, 0
	v_mov_b32_e32 v82, 0
	v_mov_b32_e32 v146, 0
	v_mov_b32_e32 v83, 0
	v_mov_b32_e32 v147, 0
	v_mov_b32_e32 v84, 0
	v_mov_b32_e32 v148, 0
	v_mov_b32_e32 v85, 0
	v_mov_b32_e32 v149, 0
	v_mov_b32_e32 v86, 0
	v_mov_b32_e32 v150, 0
	v_mov_b32_e32 v87, 0
	v_mov_b32_e32 v151, 0
	v_mov_b32_e32 v88, 0
	v_mov_b32_e32 v152, 0
	v_mov_b32_e32 v89, 0
	v_mov_b32_e32 v153, 0
	v_mov_b32_e32 v90, 0
	v_mov_b32_e32 v154, 0
	v_mov_b32_e32 v91, 0
	v_mov_b32_e32 v155, 0
	v_mov_b32_e32 v92, 0
	v_mov_b32_e32 v156, 0
	v_mov_b32_e32 v93, 0
	v_mov_b32_e32 v157, 0
	v_mov_b32_e32 v94, 0
	v_mov_b32_e32 v158, 0
	v_mov_b32_e32 v95, 0
	v_mov_b32_e32 v159, 0
	v_mov_b32_e32 v96, 0
	v_mov_b32_e32 v160, 0
	v_mov_b32_e32 v97, 0
	v_mov_b32_e32 v161, 0
	v_mov_b32_e32 v98, 0
	v_mov_b32_e32 v162, 0
	v_mov_b32_e32 v99, 0
	v_mov_b32_e32 v163, 0
	v_mov_b32_e32 v100, 0
	v_mov_b32_e32 v164, 0
	v_mov_b32_e32 v101, 0
	v_mov_b32_e32 v165, 0
	v_mov_b32_e32 v102, 0
	v_mov_b32_e32 v166, 0
	v_mov_b32_e32 v103, 0
	v_mov_b32_e32 v167, 0
	v_mov_b32_e32 v104, 0
	v_mov_b32_e32 v168, 0
	v_mov_b32_e32 v105, 0
	v_mov_b32_e32 v169, 0
	v_mov_b32_e32 v106, 0
	v_mov_b32_e32 v170, 0
	v_mov_b32_e32 v107, 0
	v_mov_b32_e32 v171, 0
	v_mov_b32_e32 v108, 0
	v_mov_b32_e32 v172, 0
	v_mov_b32_e32 v109, 0
	v_mov_b32_e32 v173, 0
	v_mov_b32_e32 v110, 0
	v_mov_b32_e32 v174, 0
	v_mov_b32_e32 v111, 0
	v_mov_b32_e32 v175, 0
	v_mov_b32_e32 v112, 0
	v_cmp_eq_u32_e64 s[28:29], 0, v27
	s_nop 1
	v_cndmask_b32_e64 v176, 0, 1.0, s[28:29]
	v_mov_b32_e32 v113, 0
	v_cmp_eq_u32_e64 s[28:29], 1, v27
	s_nop 1
	v_cndmask_b32_e64 v177, 0, 1.0, s[28:29]
	v_mov_b32_e32 v114, 0
	v_cmp_eq_u32_e64 s[28:29], 2, v27
	s_nop 1
	v_cndmask_b32_e64 v178, 0, 1.0, s[28:29]
	v_mov_b32_e32 v115, 0
	v_cmp_eq_u32_e64 s[28:29], 3, v27
	s_nop 1
	v_cndmask_b32_e64 v179, 0, 1.0, s[28:29]
	v_mov_b32_e32 v116, 0
	v_cmp_eq_u32_e64 s[28:29], 8, v27
	s_nop 1
	v_cndmask_b32_e64 v180, 0, 1.0, s[28:29]
	v_mov_b32_e32 v117, 0
	v_cmp_eq_u32_e64 s[28:29], 9, v27
	s_nop 1
	v_cndmask_b32_e64 v181, 0, 1.0, s[28:29]
	v_mov_b32_e32 v118, 0
	v_cmp_eq_u32_e64 s[28:29], 10, v27
	s_nop 1
	v_cndmask_b32_e64 v182, 0, 1.0, s[28:29]
	v_mov_b32_e32 v119, 0
	v_cmp_eq_u32_e64 s[28:29], 11, v27
	s_nop 1
	v_cndmask_b32_e64 v183, 0, 1.0, s[28:29]
	v_mov_b32_e32 v120, 0
	v_cmp_eq_u32_e64 s[28:29], 16, v27
	s_nop 1
	v_cndmask_b32_e64 v184, 0, 1.0, s[28:29]
	v_mov_b32_e32 v121, 0
	v_cmp_eq_u32_e64 s[28:29], 17, v27
	s_nop 1
	v_cndmask_b32_e64 v185, 0, 1.0, s[28:29]
	v_mov_b32_e32 v122, 0
	v_cmp_eq_u32_e64 s[28:29], 18, v27
	s_nop 1
	v_cndmask_b32_e64 v186, 0, 1.0, s[28:29]
	v_mov_b32_e32 v123, 0
	v_cmp_eq_u32_e64 s[28:29], 19, v27
	s_nop 1
	v_cndmask_b32_e64 v187, 0, 1.0, s[28:29]
	v_mov_b32_e32 v124, 0
	v_cmp_eq_u32_e64 s[28:29], 24, v27
	s_nop 1
	v_cndmask_b32_e64 v188, 0, 1.0, s[28:29]
	v_mov_b32_e32 v125, 0
	v_cmp_eq_u32_e64 s[28:29], 25, v27
	s_nop 1
	v_cndmask_b32_e64 v189, 0, 1.0, s[28:29]
	v_mov_b32_e32 v126, 0
	v_cmp_eq_u32_e64 s[28:29], 26, v27
	s_nop 1
	v_cndmask_b32_e64 v190, 0, 1.0, s[28:29]
	v_mov_b32_e32 v127, 0
	v_cmp_eq_u32_e64 s[28:29], 27, v27
	s_nop 1
	v_cndmask_b32_e64 v191, 0, 1.0, s[28:29]
	global_load_ushort v192, v3, s[4:5] offset:1024
	global_load_ushort v193, v4, s[6:7]
	global_load_ushort v194, v4, s[8:9]
	global_load_ushort v195, v4, s[10:11]
	v_add_u32_e32 v3, 0xc00, v3
	v_add_u32_e32 v4, 0x400, v4
	global_load_ushort v196, v3, s[4:5] offset:1024
	global_load_ushort v197, v4, s[6:7]
	global_load_ushort v198, v4, s[8:9]
	global_load_ushort v199, v4, s[10:11]
	v_add_u32_e32 v3, 0xc00, v3
	v_add_u32_e32 v4, 0x400, v4
	global_load_ushort v200, v3, s[4:5] offset:1024
	global_load_ushort v201, v4, s[6:7]
	global_load_ushort v202, v4, s[8:9]
	global_load_ushort v203, v4, s[10:11]
	v_add_u32_e32 v3, 0xc00, v3
	v_add_u32_e32 v4, 0x400, v4
	global_load_ushort v204, v3, s[4:5] offset:1024
	global_load_ushort v205, v4, s[6:7]
	global_load_ushort v206, v4, s[8:9]
	global_load_ushort v207, v4, s[10:11]
	v_add_u32_e32 v3, 0xc00, v3
	v_add_u32_e32 v4, 0x400, v4
	s_waitcnt vmcnt(0)
; DI float bf2f(bf16_t b) { return __uint_as_float(((unsigned)b) << 16); }
; DI float rl(float x, int l) { return __int_as_float(__builtin_amdgcn_readlane(__float_as_int(x), l)); }
; template <bool PASS2>
; DI void rwkv_item(const Params& p, int l, int item, int lane, const bf16_t* rkv, const bf16_t* lo2, float* rwst) {
;     ...
;   auto derive = [&](const Raw& x, float rpp, float kpp) __attribute__((always_inline)) {
;     Der d;
;     const float rp = bf2f(x.rp), kp = bf2f(x.kp), a = bf2f(x.a);
;     d.rr = rp + (rpp - rp) * mu_r;
;     const float k = kp + (kpp - kp) * mu_k;
;     d.wdec = __expf(-bf2f(x.ew));
;     float kkv = k * kkw;
;     const float nrm = wave_sum(kkv * kkv);
;     kkv *= rsqrtf(fmaxf(nrm, 1e-24f));
;     d.kf = k * (1.f + (a - 1.f) * kaw);
;     d.av = -kkv; d.bv = kkv * a;
;     d.v = bf2f(x.v); d.gg = bf2f(x.g);
;     return d;
;   };
;   Raw rawB = load_raw(tok0);
;   Der cur = derive(rawB, rp_prev, kp_prev);
;   float rpA = bf2f(rawB.rp), kpA = bf2f(rawB.kp);
;   rawB = load_raw(tok0 + 1);
; #pragma unroll 1
;   for (int t = 0; t < LCR; t++) {
;     Raw rawC = rawB;
;     if (t + 2 < LCR) rawC = load_raw(tok0 + t + 2);
;     Der nxt = cur;
;     if (t + 1 < LCR) nxt = derive(rawB, rpA, kpA);
;     const float rr = cur.rr, wdec = cur.wdec, kf = cur.kf, av = cur.av, bv = cur.bv, v = cur.v, gg = cur.gg;
;     float sa0 = 0.f, sa1 = 0.f, pa0 = 0.f, pa1 = 0.f;
; #pragma unroll
;     for (int j = 0; j < 64; j += 2) {
;       const float a0 = rl(av, j), a1 = rl(av, j + 1);
;       sa0 += S[j] * a0; sa1 += S[j + 1] * a1;
;       if (!PASS2) { pa0 += P[j] * a0; pa1 += P[j + 1] * a1; }
;     }
;     const float sa = sa0 + sa1, pa = pa0 + pa1;
	v_lshlrev_b32_e32 v6, 16, v6
	v_lshlrev_b32_e32 v7, 16, v7
	v_mov_b32_e32 v8, 1.0
	s_movk_i32 s36, 0x7fff
	v_lshlrev_b32_e32 v27, 16, v192
	v_sub_f32_e32 v29, v7, v27
	v_fma_f32 v29, v29, v10, v27
	v_mov_b32_e32 v7, v27
	v_lshlrev_b32_e32 v30, 16, v194
	v_mul_f32_e32 v30, 0xbfb8aa3b, v30
	v_exp_f32_e32 v30, v30
	v_lshlrev_b32_e32 v31, 16, v195
	v_mul_f32_e32 v211, v29, v11
	v_add_f32_e32 v212, -1.0, v31
	v_fma_f32 v212, v212, v12, 1.0
	v_mul_f32_e32 v212, v29, v212
	v_mul_f32_e32 v213, v211, v211
	v_mov_b32_e32 v214, 0
	v_lshlrev_b32_e32 v20, 16, v193
	s_nop 1
	v_permlane32_swap_b32 v213, v214
	s_nop 0
	v_add_f32_e32 v213, v213, v214
	s_nop 1
	v_add_f32_dpp v213, v213, v213 quad_perm:[1,0,3,2] row_mask:0xf bank_mask:0xf
	s_nop 1
	v_add_f32_dpp v213, v213, v213 quad_perm:[2,3,0,1] row_mask:0xf bank_mask:0xf
	s_nop 1
	v_add_f32_dpp v213, v213, v213 row_half_mirror row_mask:0xf bank_mask:0xf
	s_nop 1
	v_add_f32_dpp v213, v213, v213 row_mirror row_mask:0xf bank_mask:0xf
	s_nop 1
	v_add_f32_dpp v213, v213, v213 row_bcast:15 row_mask:0xa bank_mask:0xf
	s_nop 1
	v_readlane_b32 s28, v213, 31
	v_readlane_b32 s30, v213, 63
	s_nop 1
	v_mov_b32_e32 v215, s28
	v_max_f32_e32 v215, 0x179abe15, v215
	v_rsq_f32_e32 v215, v215
	v_mov_b32_e32 v19, v20
	v_mul_f32_e32 v211, v211, v215
	v_mul_f32_e64 v24, -v211, v8
	v_mul_f32_e32 v216, v211, v31
	v_mul_f32_e32 v8, v8, v30
	v_rcp_f32_e32 v217, v8
	s_nop 0
	v_mul_f32_e32 v16, v216, v217
	v_mul_f32_e32 v17, v212, v217
	ds_write_b32 v1, v16 offset:256
	s_nop 1
	v_permlane32_swap_b32 v16, v17
	ds_write_b32 v1, v24
	ds_read_b128 v[32:35], v2 offset:0
	ds_read_b128 v[36:39], v2 offset:32
	ds_read_b128 v[40:43], v2 offset:64
	ds_read_b128 v[44:47], v2 offset:96
	ds_read_b128 v[48:51], v2 offset:128
	ds_read_b128 v[52:55], v2 offset:160
	ds_read_b128 v[56:59], v2 offset:192
	ds_read_b128 v[60:63], v2 offset:224
	s_waitcnt lgkmcnt(7)
	v_pk_mul_f32 v[220:221], v[64:65], v[32:33]
	v_pk_mul_f32 v[224:225], v[128:129], v[32:33]
	v_pk_mul_f32 v[222:223], v[80:81], v[32:33]
	v_pk_mul_f32 v[226:227], v[144:145], v[32:33]
	v_pk_fma_f32 v[220:221], v[66:67], v[34:35], v[220:221]
	v_pk_fma_f32 v[224:225], v[130:131], v[34:35], v[224:225]
	v_pk_fma_f32 v[222:223], v[82:83], v[34:35], v[222:223]
	v_pk_fma_f32 v[226:227], v[146:147], v[34:35], v[226:227]
	s_waitcnt lgkmcnt(6)
	v_pk_fma_f32 v[220:221], v[68:69], v[36:37], v[220:221]
	v_pk_fma_f32 v[224:225], v[132:133], v[36:37], v[224:225]
	v_pk_fma_f32 v[222:223], v[84:85], v[36:37], v[222:223]
	v_pk_fma_f32 v[226:227], v[148:149], v[36:37], v[226:227]
	v_pk_fma_f32 v[220:221], v[70:71], v[38:39], v[220:221]
	v_pk_fma_f32 v[224:225], v[134:135], v[38:39], v[224:225]
	v_pk_fma_f32 v[222:223], v[86:87], v[38:39], v[222:223]
	v_pk_fma_f32 v[226:227], v[150:151], v[38:39], v[226:227]
	s_waitcnt lgkmcnt(5)
	v_pk_fma_f32 v[220:221], v[72:73], v[40:41], v[220:221]
	v_pk_fma_f32 v[224:225], v[136:137], v[40:41], v[224:225]
	v_pk_fma_f32 v[222:223], v[88:89], v[40:41], v[222:223]
	v_pk_fma_f32 v[226:227], v[152:153], v[40:41], v[226:227]
	v_pk_fma_f32 v[220:221], v[74:75], v[42:43], v[220:221]
	v_pk_fma_f32 v[224:225], v[138:139], v[42:43], v[224:225]
	v_pk_fma_f32 v[222:223], v[90:91], v[42:43], v[222:223]
	v_pk_fma_f32 v[226:227], v[154:155], v[42:43], v[226:227]
	s_waitcnt lgkmcnt(4)
	v_pk_fma_f32 v[220:221], v[76:77], v[44:45], v[220:221]
	v_pk_fma_f32 v[224:225], v[140:141], v[44:45], v[224:225]
	v_pk_fma_f32 v[222:223], v[92:93], v[44:45], v[222:223]
	v_pk_fma_f32 v[226:227], v[156:157], v[44:45], v[226:227]
	v_pk_fma_f32 v[220:221], v[78:79], v[46:47], v[220:221]
	v_pk_fma_f32 v[224:225], v[142:143], v[46:47], v[224:225]
	v_pk_fma_f32 v[222:223], v[94:95], v[46:47], v[222:223]
	v_pk_fma_f32 v[226:227], v[158:159], v[46:47], v[226:227]
	s_waitcnt lgkmcnt(3)
	v_pk_fma_f32 v[220:221], v[96:97], v[48:49], v[220:221]
	v_pk_fma_f32 v[224:225], v[160:161], v[48:49], v[224:225]
	v_pk_fma_f32 v[222:223], v[112:113], v[48:49], v[222:223]
	v_pk_fma_f32 v[226:227], v[176:177], v[48:49], v[226:227]
	v_pk_fma_f32 v[220:221], v[98:99], v[50:51], v[220:221]
	v_pk_fma_f32 v[224:225], v[162:163], v[50:51], v[224:225]
	v_pk_fma_f32 v[222:223], v[114:115], v[50:51], v[222:223]
	v_pk_fma_f32 v[226:227], v[178:179], v[50:51], v[226:227]
	s_waitcnt lgkmcnt(2)
	v_pk_fma_f32 v[220:221], v[100:101], v[52:53], v[220:221]
	v_pk_fma_f32 v[224:225], v[164:165], v[52:53], v[224:225]
	v_pk_fma_f32 v[222:223], v[116:117], v[52:53], v[222:223]
	v_pk_fma_f32 v[226:227], v[180:181], v[52:53], v[226:227]
	v_pk_fma_f32 v[220:221], v[102:103], v[54:55], v[220:221]
	v_pk_fma_f32 v[224:225], v[166:167], v[54:55], v[224:225]
	v_pk_fma_f32 v[222:223], v[118:119], v[54:55], v[222:223]
	v_pk_fma_f32 v[226:227], v[182:183], v[54:55], v[226:227]
	s_waitcnt lgkmcnt(1)
	v_pk_fma_f32 v[220:221], v[104:105], v[56:57], v[220:221]
	v_pk_fma_f32 v[224:225], v[168:169], v[56:57], v[224:225]
	v_pk_fma_f32 v[222:223], v[120:121], v[56:57], v[222:223]
	v_pk_fma_f32 v[226:227], v[184:185], v[56:57], v[226:227]
	v_pk_fma_f32 v[220:221], v[106:107], v[58:59], v[220:221]
	v_pk_fma_f32 v[224:225], v[170:171], v[58:59], v[224:225]
	v_pk_fma_f32 v[222:223], v[122:123], v[58:59], v[222:223]
	v_pk_fma_f32 v[226:227], v[186:187], v[58:59], v[226:227]
	s_waitcnt lgkmcnt(0)
	v_pk_fma_f32 v[220:221], v[108:109], v[60:61], v[220:221]
	v_pk_fma_f32 v[224:225], v[172:173], v[60:61], v[224:225]
	v_pk_fma_f32 v[222:223], v[124:125], v[60:61], v[222:223]
	v_pk_fma_f32 v[226:227], v[188:189], v[60:61], v[226:227]
	v_pk_fma_f32 v[220:221], v[110:111], v[62:63], v[220:221]
	v_pk_fma_f32 v[224:225], v[174:175], v[62:63], v[224:225]
	v_pk_fma_f32 v[222:223], v[126:127], v[62:63], v[222:223]
	v_pk_fma_f32 v[226:227], v[190:191], v[62:63], v[226:227]
	v_add_f32_e32 v18, v220, v221
	v_add_f32_e32 v208, v222, v223
	s_nop 1
	v_permlane32_swap_b32 v18, v208
	s_nop 0
	v_add_f32_e32 v18, v18, v208
	v_add_f32_e32 v228, v224, v225
	v_add_f32_e32 v230, v226, v227
	v_mov_b32_e32 v229, v228
	v_mov_b32_e32 v231, v230
	s_nop 1
	v_permlane32_swap_b32 v228, v229
	v_permlane32_swap_b32 v230, v231
	v_add_f32_e32 v228, v228, v229
	v_add_f32_e32 v230, v230, v231
	s_mov_b32 s18, 0
	.p2align	6

; DI void rwkv_carry(const Params& p, float* rwst) {
;     ...
;   for (int item = wsel * gridDim.x + blockIdx.x; item < 1024; item += gridDim.x * 2) {
;     const int itu = __builtin_amdgcn_readfirstlane(item);
;     const int bh = itu >> 6, i = itu & 63;
;     float* stS = rwst + (size_t)bh * NCHR * 4096 + i * 64 + lane;
;     const float* stP = (const float*)p.yc + (size_t)bh * NCHR * 4096 + lane;
;     float v = 0.f;
;     float pc[64], sc;
; #pragma unroll
;     for (int mm = 0; mm < 64; mm++) pc[mm] = stP[mm * 64];
;     sc = stS[0];
.Lcarry0_item:
	s_and_b32 s4, s3, 7
	s_lshl_b32 s4, s4, 7
	s_lshr_b32 s5, s3, 9
	s_and_b32 s5, s5, 1
	s_lshl_b32 s5, s5, 6
	s_or_b32 s4, s4, s5
	s_bfe_u32 s5, s3, 0x60003
	s_or_b32 s4, s4, s5
	s_lshr_b32 s5, s4, 6
	s_and_b32 s4, s4, 63
	s_lshl_b32 s6, s5, 21
	s_lshl_b32 s7, s4, 8
	s_add_u32 s10, s30, s6
	s_addc_u32 s11, s31, 0
	s_add_u32 s10, s10, 0xd559000
	s_addc_u32 s11, s11, 0
	s_add_u32 s12, s10, 0x2000
	s_addc_u32 s13, s11, 0
	s_add_u32 s6, s6, s7
	s_add_u32 s14, s30, s6
	s_addc_u32 s15, s31, 0
	s_add_u32 s14, s14, 0x1d558000
	s_addc_u32 s15, s15, 0
	s_add_u32 s18, s14, 0x4000
	s_addc_u32 s19, s15, 0
	global_load_dword v4, v0, s[10:11] offset:-4096
	global_load_dword v5, v0, s[10:11] offset:-3840
	global_load_dword v6, v0, s[10:11] offset:-3584
	global_load_dword v7, v0, s[10:11] offset:-3328
	global_load_dword v8, v0, s[10:11] offset:-3072
	global_load_dword v9, v0, s[10:11] offset:-2816
	global_load_dword v10, v0, s[10:11] offset:-2560
	global_load_dword v11, v0, s[10:11] offset:-2304
	global_load_dword v12, v0, s[10:11] offset:-2048
	global_load_dword v13, v0, s[10:11] offset:-1792
	global_load_dword v14, v0, s[10:11] offset:-1536
	global_load_dword v15, v0, s[10:11] offset:-1280
	global_load_dword v16, v0, s[10:11] offset:-1024
	global_load_dword v17, v0, s[10:11] offset:-768
	global_load_dword v18, v0, s[10:11] offset:-512
	global_load_dword v19, v0, s[10:11] offset:-256
	global_load_dword v20, v0, s[10:11] offset:0
	global_load_dword v21, v0, s[10:11] offset:256
	global_load_dword v22, v0, s[10:11] offset:512
	global_load_dword v23, v0, s[10:11] offset:768
	global_load_dword v24, v0, s[10:11] offset:1024
	global_load_dword v25, v0, s[10:11] offset:1280
	global_load_dword v26, v0, s[10:11] offset:1536
	global_load_dword v27, v0, s[10:11] offset:1792
	global_load_dword v28, v0, s[10:11] offset:2048
	global_load_dword v29, v0, s[10:11] offset:2304
	global_load_dword v30, v0, s[10:11] offset:2560
	global_load_dword v31, v0, s[10:11] offset:2816
	global_load_dword v32, v0, s[10:11] offset:3072
	global_load_dword v33, v0, s[10:11] offset:3328
	global_load_dword v34, v0, s[10:11] offset:3584
	global_load_dword v35, v0, s[10:11] offset:3840
	global_load_dword v36, v0, s[12:13] offset:-4096
	global_load_dword v37, v0, s[12:13] offset:-3840
	global_load_dword v38, v0, s[12:13] offset:-3584
	global_load_dword v39, v0, s[12:13] offset:-3328
	global_load_dword v40, v0, s[12:13] offset:-3072
	global_load_dword v41, v0, s[12:13] offset:-2816
	global_load_dword v42, v0, s[12:13] offset:-2560
	global_load_dword v43, v0, s[12:13] offset:-2304
	global_load_dword v44, v0, s[12:13] offset:-2048
	global_load_dword v45, v0, s[12:13] offset:-1792
	global_load_dword v46, v0, s[12:13] offset:-1536
	global_load_dword v47, v0, s[12:13] offset:-1280
	global_load_dword v48, v0, s[12:13] offset:-1024
	global_load_dword v49, v0, s[12:13] offset:-768
	global_load_dword v50, v0, s[12:13] offset:-512
	global_load_dword v51, v0, s[12:13] offset:-256
	global_load_dword v52, v0, s[12:13] offset:0
	global_load_dword v53, v0, s[12:13] offset:256
	global_load_dword v54, v0, s[12:13] offset:512
	global_load_dword v55, v0, s[12:13] offset:768
	global_load_dword v56, v0, s[12:13] offset:1024
	global_load_dword v57, v0, s[12:13] offset:1280
	global_load_dword v58, v0, s[12:13] offset:1536
	global_load_dword v59, v0, s[12:13] offset:1792
	global_load_dword v60, v0, s[12:13] offset:2048
	global_load_dword v61, v0, s[12:13] offset:2304
	global_load_dword v62, v0, s[12:13] offset:2560
	global_load_dword v63, v0, s[12:13] offset:2816
	global_load_dword v64, v0, s[12:13] offset:3072
	global_load_dword v65, v0, s[12:13] offset:3328
	global_load_dword v66, v0, s[12:13] offset:3584
	global_load_dword v67, v0, s[12:13] offset:3840
	global_load_dword v2, v0, s[14:15]
	v_mov_b32_e32 v1, 0
	s_mov_b32 s16, 0
	.p2align	6

; DI float bf2f(bf16_t b) { return __uint_as_float(((unsigned)b) << 16); }
; DI float rl(float x, int l) { return __int_as_float(__builtin_amdgcn_readlane(__float_as_int(x), l)); }
; template <bool PASS2>
; DI void rwkv_item(const Params& p, int l, int item, int lane, const bf16_t* rkv, const bf16_t* lo2, float* rwst) {
;     ...
;   auto derive = [&](const Raw& x, float rpp, float kpp) __attribute__((always_inline)) {
;     Der d;
;     const float rp = bf2f(x.rp), kp = bf2f(x.kp), a = bf2f(x.a);
;     d.rr = rp + (rpp - rp) * mu_r;
;     const float k = kp + (kpp - kp) * mu_k;
;     d.wdec = __expf(-bf2f(x.ew));
;     float kkv = k * kkw;
;     const float nrm = wave_sum(kkv * kkv);
;     kkv *= rsqrtf(fmaxf(nrm, 1e-24f));
;     d.kf = k * (1.f + (a - 1.f) * kaw);
;     d.av = -kkv; d.bv = kkv * a;
;     d.v = bf2f(x.v); d.gg = bf2f(x.g);
;     return d;
;   };
;   Raw rawB = load_raw(tok0);
;   Der cur = derive(rawB, rp_prev, kp_prev);
;   float rpA = bf2f(rawB.rp), kpA = bf2f(rawB.kp);
;   rawB = load_raw(tok0 + 1);
; #pragma unroll 1
;   for (int t = 0; t < LCR; t++) {
;     Raw rawC = rawB;
;     if (t + 2 < LCR) rawC = load_raw(tok0 + t + 2);
;     Der nxt = cur;
;     if (t + 1 < LCR) nxt = derive(rawB, rpA, kpA);
;     const float rr = cur.rr, wdec = cur.wdec, kf = cur.kf, av = cur.av, bv = cur.bv, v = cur.v, gg = cur.gg;
;     float sa0 = 0.f, sa1 = 0.f, pa0 = 0.f, pa1 = 0.f;
; #pragma unroll
;     for (int j = 0; j < 64; j += 2) {
;       const float a0 = rl(av, j), a1 = rl(av, j + 1);
;       sa0 += S[j] * a0; sa1 += S[j + 1] * a1;
;       if (!PASS2) { pa0 += P[j] * a0; pa1 += P[j + 1] * a1; }
;     }
;     const float sa = sa0 + sa1, pa = pa0 + pa1;
;     ...
;       float s1 = y, s2 = y * y, s3 = rr * kf * rkw;
.Lrwp2a_nostate:
	global_load_ushort v160, v3, s[4:5]
	global_load_ushort v161, v3, s[4:5] offset:1024
	global_load_ushort v162, v4, s[6:7]
	global_load_ushort v163, v4, s[8:9]
	global_load_ushort v164, v4, s[10:11]
	global_load_ushort v165, v4, s[12:13]
	v_add_u32_e32 v3, 0xc00, v3
	v_add_u32_e32 v4, 0x400, v4
	global_load_ushort v166, v3, s[4:5]
	global_load_ushort v167, v3, s[4:5] offset:1024
	global_load_ushort v168, v4, s[6:7]
	global_load_ushort v169, v4, s[8:9]
	global_load_ushort v170, v4, s[10:11]
	global_load_ushort v171, v4, s[12:13]
	v_add_u32_e32 v3, 0xc00, v3
	v_add_u32_e32 v4, 0x400, v4
	global_load_ushort v172, v3, s[4:5]
	global_load_ushort v173, v3, s[4:5] offset:1024
	global_load_ushort v174, v4, s[6:7]
	global_load_ushort v175, v4, s[8:9]
	global_load_ushort v176, v4, s[10:11]
	global_load_ushort v177, v4, s[12:13]
	v_add_u32_e32 v3, 0xc00, v3
	v_add_u32_e32 v4, 0x400, v4
	global_load_ushort v178, v3, s[4:5]
	global_load_ushort v179, v3, s[4:5] offset:1024
	global_load_ushort v180, v4, s[6:7]
	global_load_ushort v181, v4, s[8:9]
	global_load_ushort v182, v4, s[10:11]
	global_load_ushort v183, v4, s[12:13]
	v_add_u32_e32 v3, 0xc00, v3
	v_add_u32_e32 v4, 0x400, v4
	s_waitcnt vmcnt(0)
	v_lshlrev_b32_e32 v6, 16, v6
	v_lshlrev_b32_e32 v7, 16, v7
	v_mov_b32_e32 v8, 1.0
	s_movk_i32 s36, 0x7fff
	v_mov_b32_e32 v207, 0x3c800000
	v_lshlrev_b32_e32 v27, 16, v161
	v_sub_f32_e32 v29, v7, v27
	v_fma_f32 v29, v29, v10, v27
	v_mov_b32_e32 v7, v27
	v_lshlrev_b32_e32 v26, 16, v160
	v_sub_f32_e32 v28, v6, v26
	v_fma_f32 v28, v28, v9, v26
	v_mov_b32_e32 v6, v26
	v_lshlrev_b32_e32 v30, 16, v163
	v_mul_f32_e32 v30, 0xbfb8aa3b, v30
	v_exp_f32_e32 v30, v30
	v_lshlrev_b32_e32 v31, 16, v164
	v_mul_f32_e32 v192, v29, v11
	v_add_f32_e32 v193, -1.0, v31
	v_fma_f32 v193, v193, v12, 1.0
	v_mul_f32_e32 v193, v29, v193
	v_mul_f32_e32 v194, v192, v192
	v_mul_f32_e32 v195, v28, v193
	v_mul_f32_e32 v195, v195, v13
	v_lshlrev_b32_e32 v22, 16, v165
	v_lshlrev_b32_e32 v20, 16, v162
	s_nop 1
	v_permlane32_swap_b32 v194, v195
	s_nop 0
	v_add_f32_e32 v194, v194, v195
	s_nop 1
	v_add_f32_dpp v194, v194, v194 quad_perm:[1,0,3,2] row_mask:0xf bank_mask:0xf
	s_nop 1
	v_add_f32_dpp v194, v194, v194 quad_perm:[2,3,0,1] row_mask:0xf bank_mask:0xf
	s_nop 1
	v_add_f32_dpp v194, v194, v194 row_half_mirror row_mask:0xf bank_mask:0xf
	s_nop 1
	v_add_f32_dpp v194, v194, v194 row_mirror row_mask:0xf bank_mask:0xf
	s_nop 1
	v_add_f32_dpp v194, v194, v194 row_bcast:15 row_mask:0xa bank_mask:0xf
	s_nop 1
	v_readlane_b32 s28, v194, 31
	v_readlane_b32 s30, v194, 63
	s_nop 1
	v_mov_b32_e32 v196, s28
	v_max_f32_e32 v196, 0x179abe15, v196
	v_rsq_f32_e32 v196, v196
	v_mov_b32_e32 v19, v20
	v_mul_f32_e32 v192, v192, v196
	v_mul_f32_e64 v24, -v192, v8
	v_mul_f32_e32 v197, v192, v31
	v_mul_f32_e32 v8, v8, v30
	v_rcp_f32_e32 v198, v8
	v_mul_f32_e32 v25, v8, v28
	v_mul_f32_e32 v16, v197, v198
	v_mul_f32_e32 v17, v193, v198
	s_nop 1
	v_permlane32_swap_b32 v16, v17
	ds_write_b32 v1, v24
	ds_write_b32 v1, v25 offset:256
	ds_read_b128 v[32:35], v2 offset:0
	ds_read_b128 v[36:39], v2 offset:32
	ds_read_b128 v[40:43], v2 offset:64
	ds_read_b128 v[44:47], v2 offset:96
	ds_read_b128 v[48:51], v2 offset:128
	ds_read_b128 v[52:55], v2 offset:160
	ds_read_b128 v[56:59], v2 offset:192
	ds_read_b128 v[60:63], v2 offset:224
	s_waitcnt lgkmcnt(7)
	v_pk_mul_f32 v[184:185], v[64:65], v[32:33]
	v_pk_mul_f32 v[186:187], v[80:81], v[32:33]
	v_pk_fma_f32 v[184:185], v[66:67], v[34:35], v[184:185]
	v_pk_fma_f32 v[186:187], v[82:83], v[34:35], v[186:187]
	s_waitcnt lgkmcnt(6)
	v_pk_fma_f32 v[184:185], v[68:69], v[36:37], v[184:185]
	v_pk_fma_f32 v[186:187], v[84:85], v[36:37], v[186:187]
	v_pk_fma_f32 v[184:185], v[70:71], v[38:39], v[184:185]
	v_pk_fma_f32 v[186:187], v[86:87], v[38:39], v[186:187]
	s_waitcnt lgkmcnt(5)
	v_pk_fma_f32 v[184:185], v[72:73], v[40:41], v[184:185]
	v_pk_fma_f32 v[186:187], v[88:89], v[40:41], v[186:187]
	v_pk_fma_f32 v[184:185], v[74:75], v[42:43], v[184:185]
	v_pk_fma_f32 v[186:187], v[90:91], v[42:43], v[186:187]
	s_waitcnt lgkmcnt(4)
	v_pk_fma_f32 v[184:185], v[76:77], v[44:45], v[184:185]
	v_pk_fma_f32 v[186:187], v[92:93], v[44:45], v[186:187]
	v_pk_fma_f32 v[184:185], v[78:79], v[46:47], v[184:185]
	v_pk_fma_f32 v[186:187], v[94:95], v[46:47], v[186:187]
	s_waitcnt lgkmcnt(3)
	v_pk_fma_f32 v[184:185], v[96:97], v[48:49], v[184:185]
	v_pk_fma_f32 v[186:187], v[112:113], v[48:49], v[186:187]
	v_pk_fma_f32 v[184:185], v[98:99], v[50:51], v[184:185]
	v_pk_fma_f32 v[186:187], v[114:115], v[50:51], v[186:187]
	s_waitcnt lgkmcnt(2)
	v_pk_fma_f32 v[184:185], v[100:101], v[52:53], v[184:185]
	v_pk_fma_f32 v[186:187], v[116:117], v[52:53], v[186:187]
	v_pk_fma_f32 v[184:185], v[102:103], v[54:55], v[184:185]
	v_pk_fma_f32 v[186:187], v[118:119], v[54:55], v[186:187]
	s_waitcnt lgkmcnt(1)
	v_pk_fma_f32 v[184:185], v[104:105], v[56:57], v[184:185]
	v_pk_fma_f32 v[186:187], v[120:121], v[56:57], v[186:187]
	v_pk_fma_f32 v[184:185], v[106:107], v[58:59], v[184:185]
	v_pk_fma_f32 v[186:187], v[122:123], v[58:59], v[186:187]
	s_waitcnt lgkmcnt(0)
	v_pk_fma_f32 v[184:185], v[108:109], v[60:61], v[184:185]
	v_pk_fma_f32 v[186:187], v[124:125], v[60:61], v[186:187]
	v_pk_fma_f32 v[184:185], v[110:111], v[62:63], v[184:185]
	v_pk_fma_f32 v[186:187], v[126:127], v[62:63], v[186:187]
	v_add_f32_e32 v18, v184, v185
	v_add_f32_e32 v200, v186, v187
	s_nop 1
	v_permlane32_swap_b32 v18, v200
	s_nop 0
	v_add_f32_e32 v18, v18, v200
	s_mov_b32 s18, 0
	.p2align	6
